# on top of previous: grid barrier followers poll the global generation word directly; per-XCD republish hop removed
# speedup vs baseline: 1.0203x; 1.0041x over previous
; DI unsigned xb_ld(unsigned* p)              { return __hip_atomic_load(p, __ATOMIC_RELAXED, __HIP_MEMORY_SCOPE_AGENT); }
; DI unsigned xb_add(unsigned* p, unsigned v) { return __hip_atomic_fetch_add(p, v, __ATOMIC_RELAXED, __HIP_MEMORY_SCOPE_AGENT); }
; #define XB_SPIN(cond, bar) do { unsigned _sp = 0; while (cond) { __builtin_amdgcn_s_sleep(1); \
;     if ((++_sp & 255u) == 0u) { if (xb_ld(&(bar)[XB_TMO])) break; if (_sp > XB_SPIN_CAP) { atomicAdd(&(bar)[XB_TMO], 1u); break; } } } } while (0)
; DI void xcd_barrier(const XcdBarrier& b) {
;     ...
;         const unsigned old = xb_add(&bar[XB_XSUB(b.x)], 1u);
;         const unsigned gen = old / nloc;
;         if (old + 1u == (gen + 1u) * nloc) {
;             __builtin_amdgcn_fence(__ATOMIC_RELEASE, "agent");
;             asm volatile("s_waitcnt vmcnt(0)" ::: "memory");
;             const unsigned og = xb_add(&bar[XB_TOP], 1u);
;             const unsigned tg = og / nx;
;             if (og + 1u == (tg + 1u) * nx) xb_add(&bar[XB_TOPGEN], 1u);
;             else XB_SPIN(xb_ld(&bar[XB_TOPGEN]) == tg, bar);
;             __builtin_amdgcn_fence(__ATOMIC_ACQUIRE, "agent");
;             xb_add(&bar[XB_XGEN(b.x)], 1u);
;             asm volatile("s_waitcnt vmcnt(0)" ::: "memory");
;         } else {
;             XB_SPIN(xb_ld(&bar[XB_XGEN(b.x)]) == gen, bar);
.LBB0_965:
	s_or_b64 exec, exec, s[4:5]
	v_cvt_f32_u32_e32 v5, v3
	s_waitcnt vmcnt(0)
	v_readfirstlane_b32 s4, v4
	v_sub_u32_e32 v4, 0, v3
	v_rcp_iflag_f32_e32 v5, v5
	v_add_u32_e32 v6, s4, v0
	v_mul_f32_e32 v5, 0x4f7ffffe, v5
	v_cvt_u32_f32_e32 v5, v5
	v_mul_lo_u32 v0, v4, v5
	v_mul_hi_u32 v0, v5, v0
	v_add_u32_e32 v0, v5, v0
	v_mul_hi_u32 v0, v6, v0
	v_mul_lo_u32 v4, v0, v3
	v_sub_u32_e32 v4, v6, v4
	v_add_u32_e32 v5, 1, v0
	v_cmp_ge_u32_e32 vcc, v4, v3
	s_nop 1
	v_cndmask_b32_e32 v0, v0, v5, vcc
	v_sub_u32_e32 v5, v4, v3
	v_cndmask_b32_e32 v4, v4, v5, vcc
	v_add_u32_e32 v5, 1, v0
	v_cmp_ge_u32_e32 vcc, v4, v3
	v_add_u32_e32 v4, 1, v6
	s_nop 0
	v_cndmask_b32_e32 v0, v0, v5, vcc
	v_mul_lo_u32 v5, v3, v0
	v_add_u32_e32 v3, v5, v3
	v_cmp_ne_u32_e32 vcc, v4, v3
	s_and_saveexec_b64 s[4:5], vcc
	s_xor_b64 s[4:5], exec, s[4:5]
	s_cbranch_execz .LBB0_979
	v_readlane_b32 s6, v252, 63
	v_readlane_b32 s7, v253, 0
	s_waitcnt lgkmcnt(0)
	s_nop 3
	global_load_dword v2, v1, s[6:7] sc1
	s_waitcnt vmcnt(0)
	v_cmp_eq_u32_e32 vcc, v2, v0
	s_and_saveexec_b64 s[6:7], vcc
	s_cbranch_execz .LBB0_978
	s_mov_b32 s19, 1
	s_mov_b64 s[8:9], 0
	s_branch .LBB0_969

; DI unsigned xb_add(unsigned* p, unsigned v) { return __hip_atomic_fetch_add(p, v, __ATOMIC_RELAXED, __HIP_MEMORY_SCOPE_AGENT); }
; DI void xcd_barrier(const XcdBarrier& b) {
;     ...
;             __builtin_amdgcn_fence(__ATOMIC_ACQUIRE, "agent");
;             xb_add(&bar[XB_XGEN(b.x)], 1u);
;             asm volatile("s_waitcnt vmcnt(0)" ::: "memory");
.LBB0_1000:
	s_or_b64 exec, exec, s[4:5]
	s_mov_b64 s[4:5], exec
	v_mbcnt_lo_u32_b32 v0, s4, 0
	v_mbcnt_hi_u32_b32 v0, s5, v0
	v_cmp_eq_u32_e32 vcc, 0, v0
	s_waitcnt vmcnt(0)
	buffer_inv sc1
	s_and_saveexec_b64 s[6:7], vcc
	s_cbranch_execz .LBB0_1002
	s_bcnt1_i32_b64 s4, s[4:5]
	v_mov_b32_e32 v0, s4
	v_readlane_b32 s4, v252, 59
	v_readlane_b32 s5, v252, 60
	s_nop 4
.LBB0_1002:
	s_or_b64 exec, exec, s[6:7]
	s_waitcnt vmcnt(0)
